# v71 + work-queue atomic issued mid-item (after the unit's prologue drain / at conv item start) and consumed at item end, so no wave waits on it at item start
# speedup vs baseline: 1.0064x; 1.0063x over previous
.LBB0_507:
	s_cmp_lg_u32 s88, 0x100
	s_cbranch_scc1 .Lp3_attn
	v_readlane_b32 s2, v248, 5
	s_mul_hi_u32 s0, s6, 0xcccccccd
	s_lshr_b32 s0, s0, 2
	s_mul_i32 s1, s0, 5
	s_sub_i32 s1, s6, s1
	s_and_b32 s2, s2, 7
	s_cmp_eq_u32 s1, 4
	s_cbranch_scc0 .Lp3_dec_attn
	s_lshl_b32 s2, s2, 5
	s_add_i32 s0, s0, s2
	s_branch .Lp3_conv

.LBB0_550:
	s_or_b64 exec, exec, s[0:1]
	v_add_u32_e32 v0, 1, v128
	v_cvt_f32_u32_e32 v0, v0
	v_mov_b32_e32 v95, v97
	v_mov_b32_e32 v97, v103
	v_mov_b32_e32 v79, v85
	v_exp_f32_e64 v0, -v0
	v_mov_b32_e32 v85, v101
	v_mov_b32_e32 v87, v93
	v_mov_b32_e32 v93, v113
	v_mul_f32_e32 v118, 0x3fb8aa3b, v0
	v_add_f32_e32 v0, v99, v102
	v_fmamk_f32 v0, v0, 0x3c800000, v154
	v_rsq_f32_e32 v0, v0
	v_mov_b32_e32 v99, v67
	v_mov_b32_e32 v77, v89
	v_mov_b32_e32 v89, v117
	v_mul_f32_e32 v0, 0x3e38aa3b, v0
	s_waitcnt vmcnt(0)
	s_and_saveexec_b64 s[0:1], s[96:97]
	s_cbranch_execz .Lqd_skip_attn
	v_mov_b32_e32 v204, 1
	v_mov_b32_e32 v205, 0
	v_readlane_b32 s4, v249, 57
	v_readlane_b32 s5, v249, 58
	s_nop 4
	global_atomic_add v203, v205, v204, s[4:5] sc0
.Lqd_skip_attn:
	s_or_b64 exec, exec, s[0:1]
	v_pk_mul_f32 v[34:35], v[0:1], v[98:99] op_sel_hi:[0,1]
	v_pk_mul_f32 v[30:31], v[30:31], v[34:35]
	v_pk_mul_f32 v[34:35], v[0:1], v[96:97] op_sel_hi:[0,1]
	v_pk_mul_f32 v[32:33], v[32:33], v[34:35]
	v_pk_mul_f32 v[34:35], v[0:1], v[84:85] op_sel_hi:[0,1]
	v_pk_mul_f32 v[26:27], v[26:27], v[34:35]
	v_mov_b32_e32 v75, v109
	v_cvt_pk_bf16_f32 v84, v26, v27
	v_pk_mul_f32 v[26:27], v[0:1], v[94:95] op_sel_hi:[0,1]
	v_pk_mul_f32 v[22:23], v[22:23], v[26:27]
	v_pk_mul_f32 v[26:27], v[0:1], v[92:93] op_sel_hi:[0,1]
	v_pk_mul_f32 v[24:25], v[24:25], v[26:27]
	v_pk_mul_f32 v[26:27], v[0:1], v[88:89] op_sel_hi:[0,1]
	v_pk_mul_f32 v[18:19], v[18:19], v[26:27]
	v_mov_b32_e32 v71, v105
	v_cvt_pk_bf16_f32 v88, v18, v19
	v_pk_mul_f32 v[18:19], v[0:1], v[90:91] op_sel_hi:[0,1]
	v_pk_mul_f32 v[14:15], v[14:15], v[18:19]
	v_pk_mul_f32 v[18:19], v[0:1], v[80:81] op_sel_hi:[0,1]
	v_pk_mul_f32 v[16:17], v[16:17], v[18:19]
	v_pk_mul_f32 v[18:19], v[0:1], v[78:79] op_sel_hi:[0,1]
	v_pk_mul_f32 v[10:11], v[10:11], v[18:19]
	v_mov_b32_e32 v83, v111
	v_cvt_pk_bf16_f32 v92, v10, v11
	v_pk_mul_f32 v[10:11], v[0:1], v[74:75] op_sel_hi:[0,1]
	v_pk_mul_f32 v[6:7], v[6:7], v[10:11]
	v_pk_mul_f32 v[10:11], v[0:1], v[72:73] op_sel_hi:[0,1]
	v_pk_mul_f32 v[8:9], v[8:9], v[10:11]
	v_pk_mul_f32 v[10:11], v[0:1], v[70:71] op_sel_hi:[0,1]
	v_lshlrev_b32_e32 v119, 2, v170
	v_pk_mul_f32 v[34:35], v[0:1], v[82:83] op_sel_hi:[0,1]
	v_pk_mul_f32 v[26:27], v[0:1], v[86:87] op_sel_hi:[0,1]
	v_pk_mul_f32 v[18:19], v[0:1], v[76:77] op_sel_hi:[0,1]
	v_pk_mul_f32 v[2:3], v[2:3], v[10:11]
	v_pk_mul_f32 v[10:11], v[0:1], v[68:69] op_sel_hi:[0,1]
	v_or_b32_e32 v0, 1, v119
	v_cvt_pk_bf16_f32 v96, v2, v3
	v_cvt_f32_ubyte0_e32 v2, v119
	v_cvt_f32_ubyte0_e32 v3, v0
	v_pk_mul_f32 v[28:29], v[28:29], v[34:35]
	v_pk_mul_f32 v[34:35], v[118:119], v[2:3] op_sel_hi:[0,1]
	v_or_b32_e32 v0, 3, v119
	v_or_b32_e32 v2, 2, v119
	v_cvt_f32_ubyte0_e32 v3, v0
	v_cvt_f32_ubyte0_e32 v2, v2
	v_pk_mul_f32 v[36:37], v[118:119], v[2:3] op_sel_hi:[0,1]
	v_or_b32_e32 v0, 9, v119
	v_or_b32_e32 v2, 8, v119
	v_cvt_f32_ubyte0_e32 v3, v0
	v_cvt_f32_ubyte0_e32 v2, v2
	v_pk_mul_f32 v[38:39], v[118:119], v[2:3] op_sel_hi:[0,1]
	v_or_b32_e32 v0, 11, v119
	v_or_b32_e32 v2, 10, v119
	v_cvt_f32_ubyte0_e32 v3, v0
	v_cvt_f32_ubyte0_e32 v2, v2
	v_or_b32_e32 v0, 17, v119
	v_or_b32_e32 v98, 16, v119
	v_pk_mul_f32 v[40:41], v[118:119], v[2:3] op_sel_hi:[0,1]
	v_cvt_f32_ubyte0_e32 v3, v0
	v_cvt_f32_ubyte0_e32 v2, v98
	v_pk_mul_f32 v[42:43], v[118:119], v[2:3] op_sel_hi:[0,1]
	v_or_b32_e32 v0, 19, v119
	v_or_b32_e32 v2, 18, v119
	v_cvt_f32_ubyte0_e32 v3, v0
	v_cvt_f32_ubyte0_e32 v2, v2
	v_pk_mul_f32 v[44:45], v[118:119], v[2:3] op_sel_hi:[0,1]
	v_or_b32_e32 v0, 25, v119
	v_or_b32_e32 v2, 24, v119
	v_cvt_f32_ubyte0_e32 v3, v0
	v_cvt_f32_ubyte0_e32 v2, v2
	v_or_b32_e32 v0, 27, v119
	v_pk_mul_f32 v[46:47], v[118:119], v[2:3] op_sel_hi:[0,1]
	v_cvt_f32_ubyte0_e32 v3, v0
	v_subrev_u32_e32 v0, 31, v66
	v_and_b32_e32 v172, 31, v106
	v_lshlrev_b32_e32 v173, 3, v170
	v_or_b32_e32 v2, 26, v119
	v_ashrrev_i32_e32 v0, 4, v0
	s_cmp_gt_u32 s79, 15
	v_and_b32_e32 v107, 63, v106
	v_pk_mul_f32 v[20:21], v[20:21], v[26:27]
	v_pk_mul_f32 v[12:13], v[12:13], v[18:19]
	v_pk_mul_f32 v[4:5], v[4:5], v[10:11]
	v_cvt_f32_ubyte0_e32 v2, v2
	v_sub_u32_e32 v103, v0, v119
	s_cselect_b64 s[4:5], -1, 0
	s_cmp_lt_u32 s79, 16
	v_mad_u32_u24 v0, v172, s34, v173
	v_cvt_pk_bf16_f32 v82, v30, v31
	v_cvt_pk_bf16_f32 v83, v32, v33
	v_cvt_pk_bf16_f32 v85, v28, v29
	v_cvt_pk_bf16_f32 v86, v22, v23
	v_cvt_pk_bf16_f32 v87, v24, v25
	v_cvt_pk_bf16_f32 v89, v20, v21
	v_cvt_pk_bf16_f32 v90, v14, v15
	v_cvt_pk_bf16_f32 v91, v16, v17
	v_cvt_pk_bf16_f32 v93, v12, v13
	v_cvt_pk_bf16_f32 v94, v6, v7
	v_cvt_pk_bf16_f32 v95, v8, v9
	v_cvt_pk_bf16_f32 v97, v4, v5
	v_pk_mul_f32 v[48:49], v[118:119], v[2:3] op_sel_hi:[0,1]
	s_cselect_b64 s[6:7], -1, 0
	v_mul_f32_e32 v99, 0x44000000, v118
	v_cmp_gt_u32_e64 s[0:1], 32, v107
	s_cmp_lt_u32 s15, 8
	v_lshl_add_u32 v100, v0, 1, 0
	s_waitcnt lgkmcnt(0)
	s_barrier
	s_cbranch_scc1 .LBB0_559
	ds_read_b128 v[2:5], v100 offset:32256
	ds_read_b128 v[6:9], v100 offset:32288
	ds_read_b128 v[10:13], v100 offset:32320
	ds_read_b128 v[50:53], v100 offset:32352
	s_waitcnt lgkmcnt(3)
	v_mfma_f32_32x32x16_bf16 v[18:33], v[2:5], v[82:85], 0
	s_mov_b64 s[2:3], -1
	s_cmpk_lt_u32 s79, 0x41
	s_waitcnt lgkmcnt(2)
	v_mfma_f32_32x32x16_bf16 v[18:33], v[6:9], v[86:89], v[18:33]
	s_waitcnt lgkmcnt(1)
	v_mfma_f32_32x32x16_bf16 v[18:33], v[10:13], v[90:93], v[18:33]
	s_waitcnt lgkmcnt(0)
	v_mfma_f32_32x32x16_bf16 v[18:33], v[50:53], v[94:97], v[18:33]
	s_cbranch_scc1 .LBB0_553
	s_nop 10
	v_pk_fma_f32 v[16:17], v[48:49], s[84:85], v[32:33] op_sel_hi:[1,0,1]
	v_pk_fma_f32 v[14:15], v[46:47], s[84:85], v[30:31] op_sel_hi:[1,0,1]
	v_pk_fma_f32 v[12:13], v[44:45], s[84:85], v[28:29] op_sel_hi:[1,0,1]
	v_pk_fma_f32 v[10:11], v[42:43], s[84:85], v[26:27] op_sel_hi:[1,0,1]
	v_pk_fma_f32 v[8:9], v[40:41], s[84:85], v[24:25] op_sel_hi:[1,0,1]
	v_pk_fma_f32 v[6:7], v[38:39], s[84:85], v[22:23] op_sel_hi:[1,0,1]
	v_pk_fma_f32 v[4:5], v[36:37], s[84:85], v[20:21] op_sel_hi:[1,0,1]
	v_pk_fma_f32 v[2:3], v[34:35], s[84:85], v[18:19] op_sel_hi:[1,0,1]
	s_mov_b64 s[2:3], 0

.Lp3_item_end:
	s_and_saveexec_b64 s[0:1], s[96:97]
	s_cbranch_execz .LBB0_502
	s_waitcnt vmcnt(8)
	v_readfirstlane_b32 s2, v203
	s_cmp_eq_u32 s88, 0x100
	s_cselect_b32 vcc_lo, 32, s88
	s_add_i32 s2, vcc_lo, s2
	s_nop 0
	v_mov_b32_e32 v164, s2
	v_readlane_b32 s2, v249, 51
	s_nop 1
	v_mov_b32_e32 v0, s2
	ds_write_b32 v0, v164
	s_branch .LBB0_502
.Lp3_conv:
	s_and_saveexec_b64 s[8:9], s[96:97]
	s_cbranch_execz .Lqd_skip_conv
	v_mov_b32_e32 v200, 1
	v_mov_b32_e32 v201, 0
	v_readlane_b32 s10, v249, 57
	v_readlane_b32 s11, v249, 58
	s_nop 4
	global_atomic_add v203, v201, v200, s[10:11] sc0
.Lqd_skip_conv:
	s_or_b64 exec, exec, s[8:9]
	v_readfirstlane_b32 s1, v202
	s_lshr_b32 s1, s1, 6
	s_lshl_b32 s52, s0, 3
	s_add_i32 s52, s52, s1
	s_lshl_b32 s20, s52, 4
	v_readlane_b32 s36, v248, 12
	v_readlane_b32 s37, v248, 13
	v_readlane_b32 s8, v249, 3
	v_readlane_b32 s9, v249, 4
	v_and_b32_e32 v2, 63, v202
	v_lshlrev_b32_e32 v3, 5, v2
	v_lshlrev_b32_e32 v2, 4, v2
	s_add_u32 s8, s8, 0x10000000
	s_addc_u32 s9, s9, 0
	s_lshl_b32 s10, s20, 11
	s_mul_i32 s11, s20, 0xc00
	s_add_u32 s12, s74, s10
	s_addc_u32 s13, s75, 0
	s_add_u32 s14, s8, s10
	s_addc_u32 s15, s9, 0
	s_add_u32 s16, s68, s11
	s_addc_u32 s17, s69, 0
	s_add_u32 s16, s16, 0x400
	s_addc_u32 s17, s17, 0
	s_and_b32 s21, s52, 0xff
	s_cmp_lg_u32 s21, 0
	s_cselect_b32 s22, 0xfffff800, 0
	s_cselect_b32 s23, -1, 0
	s_cselect_b32 s24, 0xfffff000, 0
	s_add_u32 s26, s12, s22
	s_addc_u32 s27, s13, s23
	s_add_u32 s28, s12, s24
	s_addc_u32 s29, s13, s23
	s_add_u32 s18, s36, 0x0
	s_addc_u32 s19, s37, 0
	global_load_dwordx4 v[132:135], v3, s[18:19]
	global_load_dwordx4 v[136:139], v3, s[18:19] offset:16
	s_add_u32 s18, s36, 0x1000
	s_addc_u32 s19, s37, 0
	global_load_dwordx4 v[140:143], v3, s[18:19]
	global_load_dwordx4 v[144:147], v3, s[18:19] offset:16
	s_add_u32 s18, s36, 0x2000
	s_addc_u32 s19, s37, 0
	global_load_dwordx4 v[148:151], v3, s[18:19]
	global_load_dwordx4 v[152:155], v3, s[18:19] offset:16
	s_add_u32 s18, s36, 0x800
	s_addc_u32 s19, s37, 0
	global_load_dwordx4 v[156:159], v3, s[18:19]
	global_load_dwordx4 v[160:163], v3, s[18:19] offset:16
	s_add_u32 s18, s36, 0x1800
	s_addc_u32 s19, s37, 0
	global_load_dwordx4 v[164:167], v3, s[18:19]
	global_load_dwordx4 v[168:171], v3, s[18:19] offset:16
	s_add_u32 s18, s36, 0x2800
	s_addc_u32 s19, s37, 0
	global_load_dwordx4 v[172:175], v3, s[18:19]
	global_load_dwordx4 v[176:179], v3, s[18:19] offset:16
	global_load_dwordx4 v[180:183], v2, s[26:27] nt
	global_load_dwordx4 v[184:187], v2, s[28:29] nt
	global_load_dwordx4 v[188:191], v2, s[26:27] offset:1024 nt
	global_load_dwordx4 v[196:199], v2, s[28:29] offset:1024 nt
	s_add_u32 s18, s12, 0x0
	s_addc_u32 s19, s13, 0
	s_add_u32 s30, s14, 0x0
	s_addc_u32 s31, s15, 0
	global_load_dwordx4 v[4:7], v2, s[18:19] nt
	global_load_dwordx4 v[36:39], v2, s[30:31] nt
	s_add_u32 s18, s12, 0x800
	s_addc_u32 s19, s13, 0
	s_add_u32 s30, s14, 0x800
	s_addc_u32 s31, s15, 0
	global_load_dwordx4 v[8:11], v2, s[18:19] nt
	global_load_dwordx4 v[40:43], v2, s[30:31] nt
	s_add_u32 s18, s12, 0x1000
	s_addc_u32 s19, s13, 0
	s_add_u32 s30, s14, 0x1000
	s_addc_u32 s31, s15, 0
	global_load_dwordx4 v[12:15], v2, s[18:19] nt
	global_load_dwordx4 v[44:47], v2, s[30:31] nt
	s_add_u32 s18, s12, 0x1800
	s_addc_u32 s19, s13, 0
	s_add_u32 s30, s14, 0x1800
	s_addc_u32 s31, s15, 0
	global_load_dwordx4 v[16:19], v2, s[18:19] nt
	global_load_dwordx4 v[48:51], v2, s[30:31] nt
	s_add_u32 s18, s12, 0x2000
	s_addc_u32 s19, s13, 0
	s_add_u32 s30, s14, 0x2000
	s_addc_u32 s31, s15, 0
	global_load_dwordx4 v[20:23], v2, s[18:19] nt
	global_load_dwordx4 v[52:55], v2, s[30:31] nt
	s_add_u32 s18, s12, 0x2800
	s_addc_u32 s19, s13, 0
	s_add_u32 s30, s14, 0x2800
	s_addc_u32 s31, s15, 0
	global_load_dwordx4 v[24:27], v2, s[18:19] nt
	global_load_dwordx4 v[56:59], v2, s[30:31] nt
	s_add_u32 s18, s12, 0x3000
	s_addc_u32 s19, s13, 0
	s_add_u32 s30, s14, 0x3000
	s_addc_u32 s31, s15, 0
	global_load_dwordx4 v[28:31], v2, s[18:19] nt
	global_load_dwordx4 v[60:63], v2, s[30:31] nt
	s_add_u32 s18, s12, 0x3800
	s_addc_u32 s19, s13, 0
	s_add_u32 s30, s14, 0x3800
	s_addc_u32 s31, s15, 0
	global_load_dwordx4 v[32:35], v2, s[18:19] nt
	global_load_dwordx4 v[64:67], v2, s[30:31] nt
	s_add_u32 s18, s12, 0x4000
	s_addc_u32 s19, s13, 0
	s_add_u32 s30, s14, 0x4000
	s_addc_u32 s31, s15, 0
	global_load_dwordx4 v[68:71], v2, s[18:19] nt
	global_load_dwordx4 v[100:103], v2, s[30:31] nt
	s_add_u32 s18, s12, 0x4800
	s_addc_u32 s19, s13, 0
	s_add_u32 s30, s14, 0x4800
	s_addc_u32 s31, s15, 0
	global_load_dwordx4 v[72:75], v2, s[18:19] nt
	global_load_dwordx4 v[104:107], v2, s[30:31] nt
	s_add_u32 s18, s12, 0x5000
	s_addc_u32 s19, s13, 0
	s_add_u32 s30, s14, 0x5000
	s_addc_u32 s31, s15, 0
	global_load_dwordx4 v[76:79], v2, s[18:19] nt
	global_load_dwordx4 v[108:111], v2, s[30:31] nt
	s_add_u32 s18, s12, 0x5800
	s_addc_u32 s19, s13, 0
	s_add_u32 s30, s14, 0x5800
	s_addc_u32 s31, s15, 0
	global_load_dwordx4 v[80:83], v2, s[18:19] nt
	global_load_dwordx4 v[112:115], v2, s[30:31] nt
	s_add_u32 s18, s12, 0x6000
	s_addc_u32 s19, s13, 0
	s_add_u32 s30, s14, 0x6000
	s_addc_u32 s31, s15, 0
	global_load_dwordx4 v[84:87], v2, s[18:19] nt
	global_load_dwordx4 v[116:119], v2, s[30:31] nt
	s_add_u32 s18, s12, 0x6800
	s_addc_u32 s19, s13, 0
	s_add_u32 s30, s14, 0x6800
	s_addc_u32 s31, s15, 0
	global_load_dwordx4 v[88:91], v2, s[18:19] nt
	global_load_dwordx4 v[120:123], v2, s[30:31] nt
	s_add_u32 s18, s12, 0x7000
	s_addc_u32 s19, s13, 0
	s_add_u32 s30, s14, 0x7000
	s_addc_u32 s31, s15, 0
	global_load_dwordx4 v[92:95], v2, s[18:19] nt
	global_load_dwordx4 v[124:127], v2, s[30:31] nt
	s_add_u32 s18, s12, 0x7800
	s_addc_u32 s19, s13, 0
	s_add_u32 s30, s14, 0x7800
	s_addc_u32 s31, s15, 0
	global_load_dwordx4 v[96:99], v2, s[18:19] nt
	global_load_dwordx4 v[128:131], v2, s[30:31] nt
	s_waitcnt vmcnt(16)
	s_cmp_lg_u32 s21, 0
	s_cbranch_scc1 .Lcv_nz0
	v_mov_b32_e32 v180, 0
	v_mov_b32_e32 v181, 0
	v_mov_b32_e32 v182, 0
	v_mov_b32_e32 v183, 0
	v_mov_b32_e32 v184, 0
	v_mov_b32_e32 v185, 0
	v_mov_b32_e32 v186, 0
	v_mov_b32_e32 v187, 0

.Lcv_nz1:
	v_lshlrev_b32_e32 v220, 16, v196
	v_and_b32_e32 v221, 0xffff0000, v196
	v_lshlrev_b32_e32 v222, 16, v197
	v_and_b32_e32 v223, 0xffff0000, v197
	v_lshlrev_b32_e32 v224, 16, v198
	v_and_b32_e32 v225, 0xffff0000, v198
	v_lshlrev_b32_e32 v226, 16, v199
	v_and_b32_e32 v227, 0xffff0000, v199
	v_lshlrev_b32_e32 v228, 16, v188
	v_and_b32_e32 v229, 0xffff0000, v188
	v_lshlrev_b32_e32 v230, 16, v189
	v_and_b32_e32 v231, 0xffff0000, v189
	v_lshlrev_b32_e32 v232, 16, v190
	v_and_b32_e32 v233, 0xffff0000, v190
	v_lshlrev_b32_e32 v234, 16, v191
	v_and_b32_e32 v235, 0xffff0000, v191
	v_lshlrev_b32_e32 v204, 16, v4
	v_and_b32_e32 v205, 0xffff0000, v4
	v_lshlrev_b32_e32 v206, 16, v5
	v_and_b32_e32 v207, 0xffff0000, v5
	v_lshlrev_b32_e32 v208, 16, v6
	v_and_b32_e32 v209, 0xffff0000, v6
	v_lshlrev_b32_e32 v210, 16, v7
	v_and_b32_e32 v211, 0xffff0000, v7
	v_lshlrev_b32_e32 v236, 16, v36
	v_and_b32_e32 v237, 0xffff0000, v36
	v_lshlrev_b32_e32 v238, 16, v37
	v_and_b32_e32 v239, 0xffff0000, v37
	v_lshlrev_b32_e32 v240, 16, v38
	v_and_b32_e32 v241, 0xffff0000, v38
	v_lshlrev_b32_e32 v242, 16, v39
	v_and_b32_e32 v243, 0xffff0000, v39
	v_pk_mul_f32 v[244:245], v[164:165], v[228:229]
	v_pk_fma_f32 v[244:245], v[156:157], v[220:221], v[244:245]
	v_pk_fma_f32 v[244:245], v[172:173], v[204:205], v[244:245]
	v_pk_mul_f32 v[244:245], v[244:245], v[236:237]
	v_cvt_pk_bf16_f32 v212, v244, v245
	v_pk_mul_f32 v[246:247], v[166:167], v[230:231]
	v_pk_fma_f32 v[246:247], v[158:159], v[222:223], v[246:247]
	v_pk_fma_f32 v[246:247], v[174:175], v[206:207], v[246:247]
	v_pk_mul_f32 v[246:247], v[246:247], v[238:239]
	v_cvt_pk_bf16_f32 v213, v246, v247
	v_pk_mul_f32 v[244:245], v[168:169], v[232:233]
	v_pk_fma_f32 v[244:245], v[160:161], v[224:225], v[244:245]
	v_pk_fma_f32 v[244:245], v[176:177], v[208:209], v[244:245]
	v_pk_mul_f32 v[244:245], v[244:245], v[240:241]
	v_cvt_pk_bf16_f32 v214, v244, v245
	v_pk_mul_f32 v[246:247], v[170:171], v[234:235]
	v_pk_fma_f32 v[246:247], v[162:163], v[226:227], v[246:247]
	v_pk_fma_f32 v[246:247], v[178:179], v[210:211], v[246:247]
	v_pk_mul_f32 v[246:247], v[246:247], v[242:243]
	v_cvt_pk_bf16_f32 v215, v246, v247
	s_add_u32 s18, s16, 0x400
	s_addc_u32 s19, s17, 0
	global_store_dwordx4 v2, v[212:215], s[18:19] nt
	v_lshlrev_b32_e32 v220, 16, v8
	v_and_b32_e32 v221, 0xffff0000, v8
	v_lshlrev_b32_e32 v222, 16, v9
	v_and_b32_e32 v223, 0xffff0000, v9
	v_lshlrev_b32_e32 v224, 16, v10
	v_and_b32_e32 v225, 0xffff0000, v10
	v_lshlrev_b32_e32 v226, 16, v11
	v_and_b32_e32 v227, 0xffff0000, v11
	v_lshlrev_b32_e32 v236, 16, v40
	v_and_b32_e32 v237, 0xffff0000, v40
	v_lshlrev_b32_e32 v238, 16, v41
	v_and_b32_e32 v239, 0xffff0000, v41
	v_lshlrev_b32_e32 v240, 16, v42
	v_and_b32_e32 v241, 0xffff0000, v42
	v_lshlrev_b32_e32 v242, 16, v43
	v_and_b32_e32 v243, 0xffff0000, v43
	v_pk_mul_f32 v[244:245], v[164:165], v[204:205]
	v_pk_fma_f32 v[244:245], v[156:157], v[228:229], v[244:245]
	v_pk_fma_f32 v[244:245], v[172:173], v[220:221], v[244:245]
	v_pk_mul_f32 v[244:245], v[244:245], v[236:237]
	v_cvt_pk_bf16_f32 v216, v244, v245
	v_pk_mul_f32 v[246:247], v[166:167], v[206:207]
	v_pk_fma_f32 v[246:247], v[158:159], v[230:231], v[246:247]
	v_pk_fma_f32 v[246:247], v[174:175], v[222:223], v[246:247]
	v_pk_mul_f32 v[246:247], v[246:247], v[238:239]
	v_cvt_pk_bf16_f32 v217, v246, v247
	v_pk_mul_f32 v[244:245], v[168:169], v[208:209]
	v_pk_fma_f32 v[244:245], v[160:161], v[232:233], v[244:245]
	v_pk_fma_f32 v[244:245], v[176:177], v[224:225], v[244:245]
	v_pk_mul_f32 v[244:245], v[244:245], v[240:241]
	v_cvt_pk_bf16_f32 v218, v244, v245
	v_pk_mul_f32 v[246:247], v[170:171], v[210:211]
	v_pk_fma_f32 v[246:247], v[162:163], v[234:235], v[246:247]
	v_pk_fma_f32 v[246:247], v[178:179], v[226:227], v[246:247]
	v_pk_mul_f32 v[246:247], v[246:247], v[242:243]
	v_cvt_pk_bf16_f32 v219, v246, v247
	s_add_u32 s18, s16, 0x1000
	s_addc_u32 s19, s17, 0
	global_store_dwordx4 v2, v[216:219], s[18:19] nt
	v_lshlrev_b32_e32 v228, 16, v12
	v_and_b32_e32 v229, 0xffff0000, v12
	v_lshlrev_b32_e32 v230, 16, v13
	v_and_b32_e32 v231, 0xffff0000, v13
	v_lshlrev_b32_e32 v232, 16, v14
	v_and_b32_e32 v233, 0xffff0000, v14
	v_lshlrev_b32_e32 v234, 16, v15
	v_and_b32_e32 v235, 0xffff0000, v15
	v_lshlrev_b32_e32 v236, 16, v44
	v_and_b32_e32 v237, 0xffff0000, v44
	v_lshlrev_b32_e32 v238, 16, v45
	v_and_b32_e32 v239, 0xffff0000, v45
	v_lshlrev_b32_e32 v240, 16, v46
	v_and_b32_e32 v241, 0xffff0000, v46
	v_lshlrev_b32_e32 v242, 16, v47
	v_and_b32_e32 v243, 0xffff0000, v47
	v_pk_mul_f32 v[244:245], v[164:165], v[220:221]
	v_pk_fma_f32 v[244:245], v[156:157], v[204:205], v[244:245]
	v_pk_fma_f32 v[244:245], v[172:173], v[228:229], v[244:245]
	v_pk_mul_f32 v[244:245], v[244:245], v[236:237]
	v_cvt_pk_bf16_f32 v212, v244, v245
	v_pk_mul_f32 v[246:247], v[166:167], v[222:223]
	v_pk_fma_f32 v[246:247], v[158:159], v[206:207], v[246:247]
	v_pk_fma_f32 v[246:247], v[174:175], v[230:231], v[246:247]
	v_pk_mul_f32 v[246:247], v[246:247], v[238:239]
	v_cvt_pk_bf16_f32 v213, v246, v247
	v_pk_mul_f32 v[244:245], v[168:169], v[224:225]
	v_pk_fma_f32 v[244:245], v[160:161], v[208:209], v[244:245]
	v_pk_fma_f32 v[244:245], v[176:177], v[232:233], v[244:245]
	v_pk_mul_f32 v[244:245], v[244:245], v[240:241]
	v_cvt_pk_bf16_f32 v214, v244, v245
	v_pk_mul_f32 v[246:247], v[170:171], v[226:227]
	v_pk_fma_f32 v[246:247], v[162:163], v[210:211], v[246:247]
	v_pk_fma_f32 v[246:247], v[178:179], v[234:235], v[246:247]
	v_pk_mul_f32 v[246:247], v[246:247], v[242:243]
	v_cvt_pk_bf16_f32 v215, v246, v247
	s_add_u32 s18, s16, 0x1c00
	s_addc_u32 s19, s17, 0
	global_store_dwordx4 v2, v[212:215], s[18:19] nt
	v_lshlrev_b32_e32 v204, 16, v16
	v_and_b32_e32 v205, 0xffff0000, v16
	v_lshlrev_b32_e32 v206, 16, v17
	v_and_b32_e32 v207, 0xffff0000, v17
	v_lshlrev_b32_e32 v208, 16, v18
	v_and_b32_e32 v209, 0xffff0000, v18
	v_lshlrev_b32_e32 v210, 16, v19
	v_and_b32_e32 v211, 0xffff0000, v19
	v_lshlrev_b32_e32 v236, 16, v48
	v_and_b32_e32 v237, 0xffff0000, v48
	v_lshlrev_b32_e32 v238, 16, v49
	v_and_b32_e32 v239, 0xffff0000, v49
	v_lshlrev_b32_e32 v240, 16, v50
	v_and_b32_e32 v241, 0xffff0000, v50
	v_lshlrev_b32_e32 v242, 16, v51
	v_and_b32_e32 v243, 0xffff0000, v51
	v_pk_mul_f32 v[244:245], v[164:165], v[228:229]
	v_pk_fma_f32 v[244:245], v[156:157], v[220:221], v[244:245]
	v_pk_fma_f32 v[244:245], v[172:173], v[204:205], v[244:245]
	v_pk_mul_f32 v[244:245], v[244:245], v[236:237]
	v_cvt_pk_bf16_f32 v216, v244, v245
	v_pk_mul_f32 v[246:247], v[166:167], v[230:231]
	v_pk_fma_f32 v[246:247], v[158:159], v[222:223], v[246:247]
	v_pk_fma_f32 v[246:247], v[174:175], v[206:207], v[246:247]
	v_pk_mul_f32 v[246:247], v[246:247], v[238:239]
	v_cvt_pk_bf16_f32 v217, v246, v247
	v_pk_mul_f32 v[244:245], v[168:169], v[232:233]
	v_pk_fma_f32 v[244:245], v[160:161], v[224:225], v[244:245]
	v_pk_fma_f32 v[244:245], v[176:177], v[208:209], v[244:245]
	v_pk_mul_f32 v[244:245], v[244:245], v[240:241]
	v_cvt_pk_bf16_f32 v218, v244, v245
	v_pk_mul_f32 v[246:247], v[170:171], v[234:235]
	v_pk_fma_f32 v[246:247], v[162:163], v[226:227], v[246:247]
	v_pk_fma_f32 v[246:247], v[178:179], v[210:211], v[246:247]
	v_pk_mul_f32 v[246:247], v[246:247], v[242:243]
	v_cvt_pk_bf16_f32 v219, v246, v247
	s_add_u32 s18, s16, 0x2800
	s_addc_u32 s19, s17, 0
	global_store_dwordx4 v2, v[216:219], s[18:19] nt
	v_lshlrev_b32_e32 v220, 16, v20
	v_and_b32_e32 v221, 0xffff0000, v20
	v_lshlrev_b32_e32 v222, 16, v21
	v_and_b32_e32 v223, 0xffff0000, v21
	v_lshlrev_b32_e32 v224, 16, v22
	v_and_b32_e32 v225, 0xffff0000, v22
	v_lshlrev_b32_e32 v226, 16, v23
	v_and_b32_e32 v227, 0xffff0000, v23
	v_lshlrev_b32_e32 v236, 16, v52
	v_and_b32_e32 v237, 0xffff0000, v52
	v_lshlrev_b32_e32 v238, 16, v53
	v_and_b32_e32 v239, 0xffff0000, v53
	v_lshlrev_b32_e32 v240, 16, v54
	v_and_b32_e32 v241, 0xffff0000, v54
	v_lshlrev_b32_e32 v242, 16, v55
	v_and_b32_e32 v243, 0xffff0000, v55
	v_pk_mul_f32 v[244:245], v[164:165], v[204:205]
	v_pk_fma_f32 v[244:245], v[156:157], v[228:229], v[244:245]
	v_pk_fma_f32 v[244:245], v[172:173], v[220:221], v[244:245]
	v_pk_mul_f32 v[244:245], v[244:245], v[236:237]
	v_cvt_pk_bf16_f32 v212, v244, v245
	v_pk_mul_f32 v[246:247], v[166:167], v[206:207]
	v_pk_fma_f32 v[246:247], v[158:159], v[230:231], v[246:247]
	v_pk_fma_f32 v[246:247], v[174:175], v[222:223], v[246:247]
	v_pk_mul_f32 v[246:247], v[246:247], v[238:239]
	v_cvt_pk_bf16_f32 v213, v246, v247
	v_pk_mul_f32 v[244:245], v[168:169], v[208:209]
	v_pk_fma_f32 v[244:245], v[160:161], v[232:233], v[244:245]
	v_pk_fma_f32 v[244:245], v[176:177], v[224:225], v[244:245]
	v_pk_mul_f32 v[244:245], v[244:245], v[240:241]
	v_cvt_pk_bf16_f32 v214, v244, v245
	v_pk_mul_f32 v[246:247], v[170:171], v[210:211]
	v_pk_fma_f32 v[246:247], v[162:163], v[234:235], v[246:247]
	v_pk_fma_f32 v[246:247], v[178:179], v[226:227], v[246:247]
	v_pk_mul_f32 v[246:247], v[246:247], v[242:243]
	v_cvt_pk_bf16_f32 v215, v246, v247
	s_add_u32 s18, s16, 0x3400
	s_addc_u32 s19, s17, 0
	global_store_dwordx4 v2, v[212:215], s[18:19] nt
	v_lshlrev_b32_e32 v228, 16, v24
	v_and_b32_e32 v229, 0xffff0000, v24
	v_lshlrev_b32_e32 v230, 16, v25
	v_and_b32_e32 v231, 0xffff0000, v25
	v_lshlrev_b32_e32 v232, 16, v26
	v_and_b32_e32 v233, 0xffff0000, v26
	v_lshlrev_b32_e32 v234, 16, v27
	v_and_b32_e32 v235, 0xffff0000, v27
	v_lshlrev_b32_e32 v236, 16, v56
	v_and_b32_e32 v237, 0xffff0000, v56
	v_lshlrev_b32_e32 v238, 16, v57
	v_and_b32_e32 v239, 0xffff0000, v57
	v_lshlrev_b32_e32 v240, 16, v58
	v_and_b32_e32 v241, 0xffff0000, v58
	v_lshlrev_b32_e32 v242, 16, v59
	v_and_b32_e32 v243, 0xffff0000, v59
	v_pk_mul_f32 v[244:245], v[164:165], v[220:221]
	v_pk_fma_f32 v[244:245], v[156:157], v[204:205], v[244:245]
	v_pk_fma_f32 v[244:245], v[172:173], v[228:229], v[244:245]
	v_pk_mul_f32 v[244:245], v[244:245], v[236:237]
	v_cvt_pk_bf16_f32 v216, v244, v245
	v_pk_mul_f32 v[246:247], v[166:167], v[222:223]
	v_pk_fma_f32 v[246:247], v[158:159], v[206:207], v[246:247]
	v_pk_fma_f32 v[246:247], v[174:175], v[230:231], v[246:247]
	v_pk_mul_f32 v[246:247], v[246:247], v[238:239]
	v_cvt_pk_bf16_f32 v217, v246, v247
	v_pk_mul_f32 v[244:245], v[168:169], v[224:225]
	v_pk_fma_f32 v[244:245], v[160:161], v[208:209], v[244:245]
	v_pk_fma_f32 v[244:245], v[176:177], v[232:233], v[244:245]
	v_pk_mul_f32 v[244:245], v[244:245], v[240:241]
	v_cvt_pk_bf16_f32 v218, v244, v245
	v_pk_mul_f32 v[246:247], v[170:171], v[226:227]
	v_pk_fma_f32 v[246:247], v[162:163], v[210:211], v[246:247]
	v_pk_fma_f32 v[246:247], v[178:179], v[234:235], v[246:247]
	v_pk_mul_f32 v[246:247], v[246:247], v[242:243]
	v_cvt_pk_bf16_f32 v219, v246, v247
	s_add_u32 s18, s16, 0x4000
	s_addc_u32 s19, s17, 0
	global_store_dwordx4 v2, v[216:219], s[18:19] nt
	v_lshlrev_b32_e32 v204, 16, v28
	v_and_b32_e32 v205, 0xffff0000, v28
	v_lshlrev_b32_e32 v206, 16, v29
	v_and_b32_e32 v207, 0xffff0000, v29
	v_lshlrev_b32_e32 v208, 16, v30
	v_and_b32_e32 v209, 0xffff0000, v30
	v_lshlrev_b32_e32 v210, 16, v31
	v_and_b32_e32 v211, 0xffff0000, v31
	v_lshlrev_b32_e32 v236, 16, v60
	v_and_b32_e32 v237, 0xffff0000, v60
	v_lshlrev_b32_e32 v238, 16, v61
	v_and_b32_e32 v239, 0xffff0000, v61
	v_lshlrev_b32_e32 v240, 16, v62
	v_and_b32_e32 v241, 0xffff0000, v62
	v_lshlrev_b32_e32 v242, 16, v63
	v_and_b32_e32 v243, 0xffff0000, v63
	v_pk_mul_f32 v[244:245], v[164:165], v[228:229]
	v_pk_fma_f32 v[244:245], v[156:157], v[220:221], v[244:245]
	v_pk_fma_f32 v[244:245], v[172:173], v[204:205], v[244:245]
	v_pk_mul_f32 v[244:245], v[244:245], v[236:237]
	v_cvt_pk_bf16_f32 v212, v244, v245
	v_pk_mul_f32 v[246:247], v[166:167], v[230:231]
	v_pk_fma_f32 v[246:247], v[158:159], v[222:223], v[246:247]
	v_pk_fma_f32 v[246:247], v[174:175], v[206:207], v[246:247]
	v_pk_mul_f32 v[246:247], v[246:247], v[238:239]
	v_cvt_pk_bf16_f32 v213, v246, v247
	v_pk_mul_f32 v[244:245], v[168:169], v[232:233]
	v_pk_fma_f32 v[244:245], v[160:161], v[224:225], v[244:245]
	v_pk_fma_f32 v[244:245], v[176:177], v[208:209], v[244:245]
	v_pk_mul_f32 v[244:245], v[244:245], v[240:241]
	v_cvt_pk_bf16_f32 v214, v244, v245
	v_pk_mul_f32 v[246:247], v[170:171], v[234:235]
	v_pk_fma_f32 v[246:247], v[162:163], v[226:227], v[246:247]
	v_pk_fma_f32 v[246:247], v[178:179], v[210:211], v[246:247]
	v_pk_mul_f32 v[246:247], v[246:247], v[242:243]
	v_cvt_pk_bf16_f32 v215, v246, v247
	s_add_u32 s18, s16, 0x4c00
	s_addc_u32 s19, s17, 0
	global_store_dwordx4 v2, v[212:215], s[18:19] nt
	v_lshlrev_b32_e32 v220, 16, v32
	v_and_b32_e32 v221, 0xffff0000, v32
	v_lshlrev_b32_e32 v222, 16, v33
	v_and_b32_e32 v223, 0xffff0000, v33
	v_lshlrev_b32_e32 v224, 16, v34
	v_and_b32_e32 v225, 0xffff0000, v34
	v_lshlrev_b32_e32 v226, 16, v35
	v_and_b32_e32 v227, 0xffff0000, v35
	v_lshlrev_b32_e32 v236, 16, v64
	v_and_b32_e32 v237, 0xffff0000, v64
	v_lshlrev_b32_e32 v238, 16, v65
	v_and_b32_e32 v239, 0xffff0000, v65
	v_lshlrev_b32_e32 v240, 16, v66
	v_and_b32_e32 v241, 0xffff0000, v66
	v_lshlrev_b32_e32 v242, 16, v67
	v_and_b32_e32 v243, 0xffff0000, v67
	v_pk_mul_f32 v[244:245], v[164:165], v[204:205]
	v_pk_fma_f32 v[244:245], v[156:157], v[228:229], v[244:245]
	v_pk_fma_f32 v[244:245], v[172:173], v[220:221], v[244:245]
	v_pk_mul_f32 v[244:245], v[244:245], v[236:237]
	v_cvt_pk_bf16_f32 v216, v244, v245
	v_pk_mul_f32 v[246:247], v[166:167], v[206:207]
	v_pk_fma_f32 v[246:247], v[158:159], v[230:231], v[246:247]
	v_pk_fma_f32 v[246:247], v[174:175], v[222:223], v[246:247]
	v_pk_mul_f32 v[246:247], v[246:247], v[238:239]
	v_cvt_pk_bf16_f32 v217, v246, v247
	v_pk_mul_f32 v[244:245], v[168:169], v[208:209]
	v_pk_fma_f32 v[244:245], v[160:161], v[232:233], v[244:245]
	v_pk_fma_f32 v[244:245], v[176:177], v[224:225], v[244:245]
	v_pk_mul_f32 v[244:245], v[244:245], v[240:241]
	v_cvt_pk_bf16_f32 v218, v244, v245
	v_pk_mul_f32 v[246:247], v[170:171], v[210:211]
	v_pk_fma_f32 v[246:247], v[162:163], v[234:235], v[246:247]
	v_pk_fma_f32 v[246:247], v[178:179], v[226:227], v[246:247]
	v_pk_mul_f32 v[246:247], v[246:247], v[242:243]
	v_cvt_pk_bf16_f32 v219, v246, v247
	s_add_u32 s18, s16, 0x5800
	s_addc_u32 s19, s17, 0
	global_store_dwordx4 v2, v[216:219], s[18:19] nt
	s_waitcnt vmcnt(8)
	v_lshlrev_b32_e32 v228, 16, v68
	v_and_b32_e32 v229, 0xffff0000, v68
	v_lshlrev_b32_e32 v230, 16, v69
	v_and_b32_e32 v231, 0xffff0000, v69
	v_lshlrev_b32_e32 v232, 16, v70
	v_and_b32_e32 v233, 0xffff0000, v70
	v_lshlrev_b32_e32 v234, 16, v71
	v_and_b32_e32 v235, 0xffff0000, v71
	v_lshlrev_b32_e32 v236, 16, v100
	v_and_b32_e32 v237, 0xffff0000, v100
	v_lshlrev_b32_e32 v238, 16, v101
	v_and_b32_e32 v239, 0xffff0000, v101
	v_lshlrev_b32_e32 v240, 16, v102
	v_and_b32_e32 v241, 0xffff0000, v102
	v_lshlrev_b32_e32 v242, 16, v103
	v_and_b32_e32 v243, 0xffff0000, v103
	v_pk_mul_f32 v[244:245], v[164:165], v[220:221]
	v_pk_fma_f32 v[244:245], v[156:157], v[204:205], v[244:245]
	v_pk_fma_f32 v[244:245], v[172:173], v[228:229], v[244:245]
	v_pk_mul_f32 v[244:245], v[244:245], v[236:237]
	v_cvt_pk_bf16_f32 v212, v244, v245
	v_pk_mul_f32 v[246:247], v[166:167], v[222:223]
	v_pk_fma_f32 v[246:247], v[158:159], v[206:207], v[246:247]
	v_pk_fma_f32 v[246:247], v[174:175], v[230:231], v[246:247]
	v_pk_mul_f32 v[246:247], v[246:247], v[238:239]
	v_cvt_pk_bf16_f32 v213, v246, v247
	v_pk_mul_f32 v[244:245], v[168:169], v[224:225]
	v_pk_fma_f32 v[244:245], v[160:161], v[208:209], v[244:245]
	v_pk_fma_f32 v[244:245], v[176:177], v[232:233], v[244:245]
	v_pk_mul_f32 v[244:245], v[244:245], v[240:241]
	v_cvt_pk_bf16_f32 v214, v244, v245
	v_pk_mul_f32 v[246:247], v[170:171], v[226:227]
	v_pk_fma_f32 v[246:247], v[162:163], v[210:211], v[246:247]
	v_pk_fma_f32 v[246:247], v[178:179], v[234:235], v[246:247]
	v_pk_mul_f32 v[246:247], v[246:247], v[242:243]
	v_cvt_pk_bf16_f32 v215, v246, v247
	s_add_u32 s18, s16, 0x6400
	s_addc_u32 s19, s17, 0
	global_store_dwordx4 v2, v[212:215], s[18:19] nt
	v_lshlrev_b32_e32 v204, 16, v72
	v_and_b32_e32 v205, 0xffff0000, v72
	v_lshlrev_b32_e32 v206, 16, v73
	v_and_b32_e32 v207, 0xffff0000, v73
	v_lshlrev_b32_e32 v208, 16, v74
	v_and_b32_e32 v209, 0xffff0000, v74
	v_lshlrev_b32_e32 v210, 16, v75
	v_and_b32_e32 v211, 0xffff0000, v75
	v_lshlrev_b32_e32 v236, 16, v104
	v_and_b32_e32 v237, 0xffff0000, v104
	v_lshlrev_b32_e32 v238, 16, v105
	v_and_b32_e32 v239, 0xffff0000, v105
	v_lshlrev_b32_e32 v240, 16, v106
	v_and_b32_e32 v241, 0xffff0000, v106
	v_lshlrev_b32_e32 v242, 16, v107
	v_and_b32_e32 v243, 0xffff0000, v107
	v_pk_mul_f32 v[244:245], v[164:165], v[228:229]
	v_pk_fma_f32 v[244:245], v[156:157], v[220:221], v[244:245]
	v_pk_fma_f32 v[244:245], v[172:173], v[204:205], v[244:245]
	v_pk_mul_f32 v[244:245], v[244:245], v[236:237]
	v_cvt_pk_bf16_f32 v216, v244, v245
	v_pk_mul_f32 v[246:247], v[166:167], v[230:231]
	v_pk_fma_f32 v[246:247], v[158:159], v[222:223], v[246:247]
	v_pk_fma_f32 v[246:247], v[174:175], v[206:207], v[246:247]
	v_pk_mul_f32 v[246:247], v[246:247], v[238:239]
	v_cvt_pk_bf16_f32 v217, v246, v247
	v_pk_mul_f32 v[244:245], v[168:169], v[232:233]
	v_pk_fma_f32 v[244:245], v[160:161], v[224:225], v[244:245]
	v_pk_fma_f32 v[244:245], v[176:177], v[208:209], v[244:245]
	v_pk_mul_f32 v[244:245], v[244:245], v[240:241]
	v_cvt_pk_bf16_f32 v218, v244, v245
	v_pk_mul_f32 v[246:247], v[170:171], v[234:235]
	v_pk_fma_f32 v[246:247], v[162:163], v[226:227], v[246:247]
	v_pk_fma_f32 v[246:247], v[178:179], v[210:211], v[246:247]
	v_pk_mul_f32 v[246:247], v[246:247], v[242:243]
	v_cvt_pk_bf16_f32 v219, v246, v247
	s_add_u32 s18, s16, 0x7000
	s_addc_u32 s19, s17, 0
	global_store_dwordx4 v2, v[216:219], s[18:19] nt
	v_lshlrev_b32_e32 v220, 16, v76
	v_and_b32_e32 v221, 0xffff0000, v76
	v_lshlrev_b32_e32 v222, 16, v77
	v_and_b32_e32 v223, 0xffff0000, v77
	v_lshlrev_b32_e32 v224, 16, v78
	v_and_b32_e32 v225, 0xffff0000, v78
	v_lshlrev_b32_e32 v226, 16, v79
	v_and_b32_e32 v227, 0xffff0000, v79
	v_lshlrev_b32_e32 v236, 16, v108
	v_and_b32_e32 v237, 0xffff0000, v108
	v_lshlrev_b32_e32 v238, 16, v109
	v_and_b32_e32 v239, 0xffff0000, v109
	v_lshlrev_b32_e32 v240, 16, v110
	v_and_b32_e32 v241, 0xffff0000, v110
	v_lshlrev_b32_e32 v242, 16, v111
	v_and_b32_e32 v243, 0xffff0000, v111
	v_pk_mul_f32 v[244:245], v[164:165], v[204:205]
	v_pk_fma_f32 v[244:245], v[156:157], v[228:229], v[244:245]
	v_pk_fma_f32 v[244:245], v[172:173], v[220:221], v[244:245]
	v_pk_mul_f32 v[244:245], v[244:245], v[236:237]
	v_cvt_pk_bf16_f32 v212, v244, v245
	v_pk_mul_f32 v[246:247], v[166:167], v[206:207]
	v_pk_fma_f32 v[246:247], v[158:159], v[230:231], v[246:247]
	v_pk_fma_f32 v[246:247], v[174:175], v[222:223], v[246:247]
	v_pk_mul_f32 v[246:247], v[246:247], v[238:239]
	v_cvt_pk_bf16_f32 v213, v246, v247
	v_pk_mul_f32 v[244:245], v[168:169], v[208:209]
	v_pk_fma_f32 v[244:245], v[160:161], v[232:233], v[244:245]
	v_pk_fma_f32 v[244:245], v[176:177], v[224:225], v[244:245]
	v_pk_mul_f32 v[244:245], v[244:245], v[240:241]
	v_cvt_pk_bf16_f32 v214, v244, v245
	v_pk_mul_f32 v[246:247], v[170:171], v[210:211]
	v_pk_fma_f32 v[246:247], v[162:163], v[234:235], v[246:247]
	v_pk_fma_f32 v[246:247], v[178:179], v[226:227], v[246:247]
	v_pk_mul_f32 v[246:247], v[246:247], v[242:243]
	v_cvt_pk_bf16_f32 v215, v246, v247
	s_add_u32 s18, s16, 0x7c00
	s_addc_u32 s19, s17, 0
	global_store_dwordx4 v2, v[212:215], s[18:19] nt
	v_lshlrev_b32_e32 v228, 16, v80
	v_and_b32_e32 v229, 0xffff0000, v80
	v_lshlrev_b32_e32 v230, 16, v81
	v_and_b32_e32 v231, 0xffff0000, v81
	v_lshlrev_b32_e32 v232, 16, v82
	v_and_b32_e32 v233, 0xffff0000, v82
	v_lshlrev_b32_e32 v234, 16, v83
	v_and_b32_e32 v235, 0xffff0000, v83
	v_lshlrev_b32_e32 v236, 16, v112
	v_and_b32_e32 v237, 0xffff0000, v112
	v_lshlrev_b32_e32 v238, 16, v113
	v_and_b32_e32 v239, 0xffff0000, v113
	v_lshlrev_b32_e32 v240, 16, v114
	v_and_b32_e32 v241, 0xffff0000, v114
	v_lshlrev_b32_e32 v242, 16, v115
	v_and_b32_e32 v243, 0xffff0000, v115
	v_pk_mul_f32 v[244:245], v[164:165], v[220:221]
	v_pk_fma_f32 v[244:245], v[156:157], v[204:205], v[244:245]
	v_pk_fma_f32 v[244:245], v[172:173], v[228:229], v[244:245]
	v_pk_mul_f32 v[244:245], v[244:245], v[236:237]
	v_cvt_pk_bf16_f32 v216, v244, v245
	v_pk_mul_f32 v[246:247], v[166:167], v[222:223]
	v_pk_fma_f32 v[246:247], v[158:159], v[206:207], v[246:247]
	v_pk_fma_f32 v[246:247], v[174:175], v[230:231], v[246:247]
	v_pk_mul_f32 v[246:247], v[246:247], v[238:239]
	v_cvt_pk_bf16_f32 v217, v246, v247
	v_pk_mul_f32 v[244:245], v[168:169], v[224:225]
	v_pk_fma_f32 v[244:245], v[160:161], v[208:209], v[244:245]
	v_pk_fma_f32 v[244:245], v[176:177], v[232:233], v[244:245]
	v_pk_mul_f32 v[244:245], v[244:245], v[240:241]
	v_cvt_pk_bf16_f32 v218, v244, v245
	v_pk_mul_f32 v[246:247], v[170:171], v[226:227]
	v_pk_fma_f32 v[246:247], v[162:163], v[210:211], v[246:247]
	v_pk_fma_f32 v[246:247], v[178:179], v[234:235], v[246:247]
	v_pk_mul_f32 v[246:247], v[246:247], v[242:243]
	v_cvt_pk_bf16_f32 v219, v246, v247
	s_add_u32 s18, s16, 0x8800
	s_addc_u32 s19, s17, 0
	global_store_dwordx4 v2, v[216:219], s[18:19] nt
	v_lshlrev_b32_e32 v204, 16, v84
	v_and_b32_e32 v205, 0xffff0000, v84
	v_lshlrev_b32_e32 v206, 16, v85
	v_and_b32_e32 v207, 0xffff0000, v85
	v_lshlrev_b32_e32 v208, 16, v86
	v_and_b32_e32 v209, 0xffff0000, v86
	v_lshlrev_b32_e32 v210, 16, v87
	v_and_b32_e32 v211, 0xffff0000, v87
	v_lshlrev_b32_e32 v236, 16, v116
	v_and_b32_e32 v237, 0xffff0000, v116
	v_lshlrev_b32_e32 v238, 16, v117
	v_and_b32_e32 v239, 0xffff0000, v117
	v_lshlrev_b32_e32 v240, 16, v118
	v_and_b32_e32 v241, 0xffff0000, v118
	v_lshlrev_b32_e32 v242, 16, v119
	v_and_b32_e32 v243, 0xffff0000, v119
	v_pk_mul_f32 v[244:245], v[164:165], v[228:229]
	v_pk_fma_f32 v[244:245], v[156:157], v[220:221], v[244:245]
	v_pk_fma_f32 v[244:245], v[172:173], v[204:205], v[244:245]
	v_pk_mul_f32 v[244:245], v[244:245], v[236:237]
	v_cvt_pk_bf16_f32 v212, v244, v245
	v_pk_mul_f32 v[246:247], v[166:167], v[230:231]
	v_pk_fma_f32 v[246:247], v[158:159], v[222:223], v[246:247]
	v_pk_fma_f32 v[246:247], v[174:175], v[206:207], v[246:247]
	v_pk_mul_f32 v[246:247], v[246:247], v[238:239]
	v_cvt_pk_bf16_f32 v213, v246, v247
	v_pk_mul_f32 v[244:245], v[168:169], v[232:233]
	v_pk_fma_f32 v[244:245], v[160:161], v[224:225], v[244:245]
	v_pk_fma_f32 v[244:245], v[176:177], v[208:209], v[244:245]
	v_pk_mul_f32 v[244:245], v[244:245], v[240:241]
	v_cvt_pk_bf16_f32 v214, v244, v245
	v_pk_mul_f32 v[246:247], v[170:171], v[234:235]
	v_pk_fma_f32 v[246:247], v[162:163], v[226:227], v[246:247]
	v_pk_fma_f32 v[246:247], v[178:179], v[210:211], v[246:247]
	v_pk_mul_f32 v[246:247], v[246:247], v[242:243]
	v_cvt_pk_bf16_f32 v215, v246, v247
	s_add_u32 s18, s16, 0x9400
	s_addc_u32 s19, s17, 0
	global_store_dwordx4 v2, v[212:215], s[18:19] nt
	v_lshlrev_b32_e32 v220, 16, v88
	v_and_b32_e32 v221, 0xffff0000, v88
	v_lshlrev_b32_e32 v222, 16, v89
	v_and_b32_e32 v223, 0xffff0000, v89
	v_lshlrev_b32_e32 v224, 16, v90
	v_and_b32_e32 v225, 0xffff0000, v90
	v_lshlrev_b32_e32 v226, 16, v91
	v_and_b32_e32 v227, 0xffff0000, v91
	v_lshlrev_b32_e32 v236, 16, v120
	v_and_b32_e32 v237, 0xffff0000, v120
	v_lshlrev_b32_e32 v238, 16, v121
	v_and_b32_e32 v239, 0xffff0000, v121
	v_lshlrev_b32_e32 v240, 16, v122
	v_and_b32_e32 v241, 0xffff0000, v122
	v_lshlrev_b32_e32 v242, 16, v123
	v_and_b32_e32 v243, 0xffff0000, v123
	v_pk_mul_f32 v[244:245], v[164:165], v[204:205]
	v_pk_fma_f32 v[244:245], v[156:157], v[228:229], v[244:245]
	v_pk_fma_f32 v[244:245], v[172:173], v[220:221], v[244:245]
	v_pk_mul_f32 v[244:245], v[244:245], v[236:237]
	v_cvt_pk_bf16_f32 v216, v244, v245
	v_pk_mul_f32 v[246:247], v[166:167], v[206:207]
	v_pk_fma_f32 v[246:247], v[158:159], v[230:231], v[246:247]
	v_pk_fma_f32 v[246:247], v[174:175], v[222:223], v[246:247]
	v_pk_mul_f32 v[246:247], v[246:247], v[238:239]
	v_cvt_pk_bf16_f32 v217, v246, v247
	v_pk_mul_f32 v[244:245], v[168:169], v[208:209]
	v_pk_fma_f32 v[244:245], v[160:161], v[232:233], v[244:245]
	v_pk_fma_f32 v[244:245], v[176:177], v[224:225], v[244:245]
	v_pk_mul_f32 v[244:245], v[244:245], v[240:241]
	v_cvt_pk_bf16_f32 v218, v244, v245
	v_pk_mul_f32 v[246:247], v[170:171], v[210:211]
	v_pk_fma_f32 v[246:247], v[162:163], v[234:235], v[246:247]
	v_pk_fma_f32 v[246:247], v[178:179], v[226:227], v[246:247]
	v_pk_mul_f32 v[246:247], v[246:247], v[242:243]
	v_cvt_pk_bf16_f32 v219, v246, v247
	s_add_u32 s18, s16, 0xa000
	s_addc_u32 s19, s17, 0
	global_store_dwordx4 v2, v[216:219], s[18:19] nt
	v_lshlrev_b32_e32 v228, 16, v92
	v_and_b32_e32 v229, 0xffff0000, v92
	v_lshlrev_b32_e32 v230, 16, v93
	v_and_b32_e32 v231, 0xffff0000, v93
	v_lshlrev_b32_e32 v232, 16, v94
	v_and_b32_e32 v233, 0xffff0000, v94
	v_lshlrev_b32_e32 v234, 16, v95
	v_and_b32_e32 v235, 0xffff0000, v95
	v_lshlrev_b32_e32 v236, 16, v124
	v_and_b32_e32 v237, 0xffff0000, v124
	v_lshlrev_b32_e32 v238, 16, v125
	v_and_b32_e32 v239, 0xffff0000, v125
	v_lshlrev_b32_e32 v240, 16, v126
	v_and_b32_e32 v241, 0xffff0000, v126
	v_lshlrev_b32_e32 v242, 16, v127
	v_and_b32_e32 v243, 0xffff0000, v127
	v_pk_mul_f32 v[244:245], v[164:165], v[220:221]
	v_pk_fma_f32 v[244:245], v[156:157], v[204:205], v[244:245]
	v_pk_fma_f32 v[244:245], v[172:173], v[228:229], v[244:245]
	v_pk_mul_f32 v[244:245], v[244:245], v[236:237]
	v_cvt_pk_bf16_f32 v212, v244, v245
	v_pk_mul_f32 v[246:247], v[166:167], v[222:223]
	v_pk_fma_f32 v[246:247], v[158:159], v[206:207], v[246:247]
	v_pk_fma_f32 v[246:247], v[174:175], v[230:231], v[246:247]
	v_pk_mul_f32 v[246:247], v[246:247], v[238:239]
	v_cvt_pk_bf16_f32 v213, v246, v247
	v_pk_mul_f32 v[244:245], v[168:169], v[224:225]
	v_pk_fma_f32 v[244:245], v[160:161], v[208:209], v[244:245]
	v_pk_fma_f32 v[244:245], v[176:177], v[232:233], v[244:245]
	v_pk_mul_f32 v[244:245], v[244:245], v[240:241]
	v_cvt_pk_bf16_f32 v214, v244, v245
	v_pk_mul_f32 v[246:247], v[170:171], v[226:227]
	v_pk_fma_f32 v[246:247], v[162:163], v[210:211], v[246:247]
	v_pk_fma_f32 v[246:247], v[178:179], v[234:235], v[246:247]
	v_pk_mul_f32 v[246:247], v[246:247], v[242:243]
	v_cvt_pk_bf16_f32 v215, v246, v247
	s_add_u32 s18, s16, 0xac00
	s_addc_u32 s19, s17, 0
	global_store_dwordx4 v2, v[212:215], s[18:19] nt
	v_lshlrev_b32_e32 v204, 16, v96
	v_and_b32_e32 v205, 0xffff0000, v96
	v_lshlrev_b32_e32 v206, 16, v97
	v_and_b32_e32 v207, 0xffff0000, v97
	v_lshlrev_b32_e32 v208, 16, v98
	v_and_b32_e32 v209, 0xffff0000, v98
	v_lshlrev_b32_e32 v210, 16, v99
	v_and_b32_e32 v211, 0xffff0000, v99
	v_lshlrev_b32_e32 v236, 16, v128
	v_and_b32_e32 v237, 0xffff0000, v128
	v_lshlrev_b32_e32 v238, 16, v129
	v_and_b32_e32 v239, 0xffff0000, v129
	v_lshlrev_b32_e32 v240, 16, v130
	v_and_b32_e32 v241, 0xffff0000, v130
	v_lshlrev_b32_e32 v242, 16, v131
	v_and_b32_e32 v243, 0xffff0000, v131
	v_pk_mul_f32 v[244:245], v[164:165], v[228:229]
	v_pk_fma_f32 v[244:245], v[156:157], v[220:221], v[244:245]
	v_pk_fma_f32 v[244:245], v[172:173], v[204:205], v[244:245]
	v_pk_mul_f32 v[244:245], v[244:245], v[236:237]
	v_cvt_pk_bf16_f32 v216, v244, v245
	v_pk_mul_f32 v[246:247], v[166:167], v[230:231]
	v_pk_fma_f32 v[246:247], v[158:159], v[222:223], v[246:247]
	v_pk_fma_f32 v[246:247], v[174:175], v[206:207], v[246:247]
	v_pk_mul_f32 v[246:247], v[246:247], v[238:239]
	v_cvt_pk_bf16_f32 v217, v246, v247
	v_pk_mul_f32 v[244:245], v[168:169], v[232:233]
	v_pk_fma_f32 v[244:245], v[160:161], v[224:225], v[244:245]
	v_pk_fma_f32 v[244:245], v[176:177], v[208:209], v[244:245]
	v_pk_mul_f32 v[244:245], v[244:245], v[240:241]
	v_cvt_pk_bf16_f32 v218, v244, v245
	v_pk_mul_f32 v[246:247], v[170:171], v[234:235]
	v_pk_fma_f32 v[246:247], v[162:163], v[226:227], v[246:247]
	v_pk_fma_f32 v[246:247], v[178:179], v[210:211], v[246:247]
	v_pk_mul_f32 v[246:247], v[246:247], v[242:243]
	v_cvt_pk_bf16_f32 v219, v246, v247
	s_add_u32 s18, s16, 0xb800
	s_addc_u32 s19, s17, 0
	global_store_dwordx4 v2, v[216:219], s[18:19] nt
	v_mbcnt_hi_u32_b32 v155, -1, v194
	v_and_b32_e32 v0, 64, v155
	v_mov_b32_e32 v154, 0x358637bd
	v_xor_b32_e32 v156, 32, v155
	v_add_u32_e32 v157, 64, v0
	v_mov_b32_e32 v158, 0xf149f2ca
	v_mov_b32_e32 v159, 0x7149f2ca
	v_mov_b32_e32 v160, 0x2080
	v_mov_b32_e32 v161, 0x461c4000
	v_mov_b32_e32 v162, 0xffffff80
	v_mov_b32_e32 v163, 0x63
	s_branch .Lp3_item_end
